# v48: v47 + the gate->next-layer in-proj boundary is an XCD-local barrier too (layers 0-2 only; chip-wide after the last layer)
# speedup vs baseline: 1.0077x; 1.0017x over previous
.LBB0_1090:
	s_mov_b64 s[4:5], exec
	v_readlane_b32 s99, v255, 40
	s_bitcmp1_b32 s99, 0
	s_cbranch_scc0 .Lxl_9_full
	v_readlane_b32 s99, v255, 28
	s_cmp_lg_u32 s99, 3
	s_cbranch_scc1 .Lxl_9
.Lxl_9_full:
	buffer_wbl2 sc1
	s_waitcnt lgkmcnt(0)
	s_waitcnt vmcnt(0)
	v_mbcnt_lo_u32_b32 v1, s4, 0
	v_mbcnt_hi_u32_b32 v1, s5, v1
	v_cmp_eq_u32_e32 vcc, 0, v1
	s_and_saveexec_b64 s[6:7], vcc
	s_cbranch_execz .LBB0_1092
	s_bcnt1_i32_b64 s4, s[4:5]
	v_mov_b32_e32 v2, s4
	v_readlane_b32 s4, v254, 35
	v_readlane_b32 s5, v254, 36
	s_nop 4
	global_atomic_add v2, v201, v2, s[4:5] sc0

.Lxl_9:
	s_mov_b64 s[4:5], exec
	v_mbcnt_lo_u32_b32 v0, s4, 0
	v_mbcnt_hi_u32_b32 v0, s5, v0
	v_cmp_eq_u32_e32 vcc, 0, v0
	s_waitcnt vmcnt(0)
	buffer_inv sc1
	s_and_saveexec_b64 s[6:7], vcc
	s_cbranch_execnz .LBB0_1107
	s_getpc_b64 s[98:99]
